# code placement: the three GEMM K-loop heads pinned to 64-byte boundaries with .p2align 6 (padding unreachable, after s_branch) (stacked on v16)
# speedup vs baseline: 1.0155x; 1.0155x over previous
; #define PG8_STAGE(bufoff, gbase, voff) do { _Pragma("unroll") for (int _i = 0; _i < 2; ++_i) \
;         __builtin_amdgcn_global_load_lds((const unsigned*)((const char*)(gbase) + (voff)[_i]), (LAS unsigned*)(lds + (bufoff) + ldsw + _i * 8192), 16, 0, 0); } while (0)
; #define PG8_LDA(dst, b, h) do { _Pragma("unroll") for (int m = 0; m < 4; ++m) _Pragma("unroll") for (int k = 0; k < 2; ++k) dst[m][k] = *(const LAS bf16x8*)(lds + PG8_SA(b, h) + aoff + m * 2048 + k * 1024); } while (0)
; #define PG8_LDB(dst, b, h) do { _Pragma("unroll") for (int n = 0; n < 2; ++n) _Pragma("unroll") for (int k = 0; k < 2; ++k) dst[n][k] = *(const LAS bf16x8*)(lds + PG8_SB(b, h) + boff + n * 2048 + k * 1024); } while (0)
; #define PG8_WAIT_V(n) asm volatile("s_waitcnt vmcnt(" #n ")" ::: "memory")
; #define PG8_WAIT_L(n) asm volatile("s_waitcnt lgkmcnt(" #n ")" ::: "memory")
; #define PG8_BAR __builtin_amdgcn_s_barrier()
; #define PG8_SCHED __builtin_amdgcn_sched_barrier(0)
; template <class Epi>
; DI void gemm_phase(int wv, LAS unsigned char* lds, const GemmD g, const Epi& E) {
;     ...
;         const bool has_next = S.next(ui + 1, nxt);
;         const char* nA = has_next ? (const char*)g.A + (size_t)nxt.pm * 256 * g.lda * 2 : cA; const char* nB = has_next ? (const char*)g.Bt + PG8_BROW(nxt.pn) * (size_t)g.ldb * 2 : cB;
;         for (int t = 0; t < nt; t += 2) {
;             const bool last = (t == nt - 2);
;             const char* a1 = cA + (size_t)(t + 1) * kstep;
;             const char* a2 = last ? nA : cA + (size_t)(t + 2) * kstep; const char* b2 = last ? nB : cB + (size_t)(t + 2) * kstep;
;             const char* a3 = a2 + kstep; const char* b3 = b2 + kstep;
;             PG8_LDB(B0, 0, 0); PG8_SCHED; PG8_LDA(At, 0, 0); PG8_STAGE(PG8_SA(1, 1), a1 + hstepA, voffA);
;             PG8_WAIT_L(8); PG8_BAR; PG8_WAIT_L(0); PG8_MMA(0, 0, At, B0); PG8_BAR; PG8_SCHED;
;             PG8_LDB(B1, 0, 1); PG8_STAGE(PG8_SB(0, 0), b2, voffB);
;             PG8_BAR; PG8_WAIT_L(0); PG8_MMA(0, 1, At, B1); PG8_BAR;
;             PG8_LDA(At, 0, 1); PG8_STAGE(PG8_SA(0, 0), a2, voffA);
;             PG8_BAR; PG8_WAIT_L(0); PG8_MMA(1, 0, At, B0); PG8_BAR; PG8_SCHED;
;             PG8_STAGE(PG8_SB(0, 1), b2 + hstepB, voffB);
;             PG8_WAIT_V(6); PG8_BAR; PG8_MMA(1, 1, At, B1); PG8_BAR;
.LBB0_98:
	s_ashr_i32 s17, s16, 31
	s_lshl_b64 s[20:21], s[16:17], 19
	s_add_u32 s20, s6, s20
	s_addc_u32 s21, s7, s21
	s_and_b64 s[4:5], s[4:5], exec
	s_cselect_b32 s17, s21, s25
	s_cselect_b32 vcc_lo, s20, s24
	s_add_u32 s4, s24, 0x40080
	s_addc_u32 s5, s25, 0
	s_add_u32 vcc_hi, s22, 0x100
	s_addc_u32 s75, s23, 0
	s_mov_b32 s95, -2
	s_add_u32 s22, s4, 0xfffc0080
	s_addc_u32 s23, s5, -1
	s_add_i32 s3, 0, 0x10000
	v_add_u32_e32 v156, s3, v141
	ds_read_b128 v[144:147], v156
	ds_read_b128 v[148:151], v156 offset:1024
	ds_read_b128 v[152:155], v156 offset:2048
	ds_read_b128 v[156:159], v156 offset:3072
	s_cmp_eq_u32 s95, 12
	s_cselect_b32 s23, s17, s23
	s_cselect_b32 s22, vcc_lo, s22
	s_cselect_b32 s25, s19, s75
	s_cselect_b32 s24, s18, vcc_hi
	v_lshl_add_u64 v[164:165], s[4:5], 0, v[136:137]
	s_add_i32 m0, s15, 0xc000
	ds_read_b128 v[160:163], v143
	ds_read_b128 v[176:179], v143 offset:1024
	ds_read_b128 v[180:183], v143 offset:2048
	ds_read_b128 v[184:187], v143 offset:3072
	ds_read_b128 v[188:191], v143 offset:4096
	ds_read_b128 v[192:195], v143 offset:5120
	ds_read_b128 v[196:199], v143 offset:6144
	ds_read_b128 v[200:203], v143 offset:7168
	global_load_lds_dwordx4 v[164:165], off
	v_lshl_add_u64 v[164:165], s[4:5], 0, v[138:139]
	s_add_i32 m0, s15, 0xe000
	s_nop 0
	global_load_lds_dwordx4 v[164:165], off
	s_waitcnt lgkmcnt(8)
	s_barrier
	s_waitcnt lgkmcnt(0)
	s_waitcnt lgkmcnt(0)
	v_mfma_f32_16x16x32_bf16 v[126:129], v[144:147], v[160:163], 0
	v_mfma_f32_16x16x32_bf16 v[122:125], v[152:155], v[160:163], 0
	v_mfma_f32_16x16x32_bf16 v[118:121], v[144:147], v[180:183], 0
	v_mfma_f32_16x16x32_bf16 v[114:117], v[152:155], v[180:183], 0
	v_mfma_f32_16x16x32_bf16 v[102:105], v[144:147], v[188:191], 0
	v_mfma_f32_16x16x32_bf16 v[98:101], v[152:155], v[188:191], 0
	v_mfma_f32_16x16x32_bf16 v[86:89], v[144:147], v[196:199], 0
	v_mfma_f32_16x16x32_bf16 v[82:85], v[152:155], v[196:199], 0
	v_mfma_f32_16x16x32_bf16 v[126:129], v[148:151], v[176:179], v[126:129]
	v_mfma_f32_16x16x32_bf16 v[122:125], v[156:159], v[176:179], v[122:125]
	v_mfma_f32_16x16x32_bf16 v[118:121], v[148:151], v[184:187], v[118:121]
	v_mfma_f32_16x16x32_bf16 v[114:117], v[156:159], v[184:187], v[114:117]
	v_mfma_f32_16x16x32_bf16 v[102:105], v[148:151], v[192:195], v[102:105]
	v_mfma_f32_16x16x32_bf16 v[98:101], v[156:159], v[192:195], v[98:101]
	v_mfma_f32_16x16x32_bf16 v[86:89], v[148:151], v[200:203], v[86:89]
	v_mfma_f32_16x16x32_bf16 v[82:85], v[156:159], v[200:203], v[82:85]
	s_barrier
	s_add_i32 s2, 0, 0x14000
	v_add_u32_e32 v164, s2, v141
	s_add_i32 s3, s3, s37
	ds_read_b128 v[204:207], v164
	ds_read_b128 v[208:211], v164 offset:1024
	ds_read_b128 v[212:215], v164 offset:2048
	ds_read_b128 v[216:219], v164 offset:3072
	v_lshl_add_u64 v[164:165], s[24:25], 0, v[0:1]
	s_mov_b32 m0, s3
	v_lshl_add_u64 v[168:169], s[24:25], 0, v[130:131]
	global_load_lds_dwordx4 v[164:165], off
	s_add_i32 m0, s3, 0x2000
	s_nop 0
	global_load_lds_dwordx4 v[168:169], off
	s_barrier
	s_waitcnt lgkmcnt(0)
	s_waitcnt lgkmcnt(0)
	v_mfma_f32_16x16x32_bf16 v[110:113], v[204:207], v[160:163], 0
	v_mfma_f32_16x16x32_bf16 v[106:109], v[212:215], v[160:163], 0
	v_mfma_f32_16x16x32_bf16 v[94:97], v[204:207], v[180:183], 0
	v_mfma_f32_16x16x32_bf16 v[90:93], v[212:215], v[180:183], 0
	v_mfma_f32_16x16x32_bf16 v[78:81], v[204:207], v[188:191], 0
	v_mfma_f32_16x16x32_bf16 v[74:77], v[212:215], v[188:191], 0
	v_mfma_f32_16x16x32_bf16 v[70:73], v[204:207], v[196:199], 0
	v_mfma_f32_16x16x32_bf16 v[66:69], v[212:215], v[196:199], 0
	v_mfma_f32_16x16x32_bf16 v[110:113], v[208:211], v[176:179], v[110:113]
	v_mfma_f32_16x16x32_bf16 v[106:109], v[216:219], v[176:179], v[106:109]
	v_mfma_f32_16x16x32_bf16 v[94:97], v[208:211], v[184:187], v[94:97]
	v_mfma_f32_16x16x32_bf16 v[90:93], v[216:219], v[184:187], v[90:93]
	v_mfma_f32_16x16x32_bf16 v[78:81], v[208:211], v[192:195], v[78:81]
	v_mfma_f32_16x16x32_bf16 v[74:77], v[216:219], v[192:195], v[74:77]
	v_mfma_f32_16x16x32_bf16 v[70:73], v[208:211], v[200:203], v[70:73]
	v_mfma_f32_16x16x32_bf16 v[66:69], v[216:219], v[200:203], v[66:69]
	s_mov_b32 m0, s15
	v_lshl_add_u64 v[170:171], s[22:23], 0, v[134:135]
	s_barrier
	ds_read_b128 v[160:163], v143 offset:16384
	ds_read_b128 v[176:179], v143 offset:17408
	ds_read_b128 v[180:183], v143 offset:18432
	ds_read_b128 v[184:187], v143 offset:19456
	ds_read_b128 v[188:191], v143 offset:20480
	ds_read_b128 v[192:195], v143 offset:21504
	ds_read_b128 v[196:199], v143 offset:22528
	ds_read_b128 v[200:203], v143 offset:23552
	global_load_lds_dwordx4 v[170:171], off
	v_lshl_add_u64 v[220:221], s[22:23], 0, v[132:133]
	s_mov_b32 m0, s45
	s_nop 0
	global_load_lds_dwordx4 v[220:221], off
	s_barrier
	s_waitcnt lgkmcnt(0)
	s_waitcnt lgkmcnt(0)
	v_mfma_f32_16x16x32_bf16 v[62:65], v[144:147], v[160:163], 0
	v_mfma_f32_16x16x32_bf16 v[58:61], v[152:155], v[160:163], 0
	v_mfma_f32_16x16x32_bf16 v[54:57], v[144:147], v[180:183], 0
	v_mfma_f32_16x16x32_bf16 v[50:53], v[152:155], v[180:183], 0
	v_mfma_f32_16x16x32_bf16 v[38:41], v[144:147], v[188:191], 0
	v_mfma_f32_16x16x32_bf16 v[34:37], v[152:155], v[188:191], 0
	v_mfma_f32_16x16x32_bf16 v[22:25], v[144:147], v[196:199], 0
	v_mfma_f32_16x16x32_bf16 v[18:21], v[152:155], v[196:199], 0
	v_mfma_f32_16x16x32_bf16 v[62:65], v[148:151], v[176:179], v[62:65]
	v_mfma_f32_16x16x32_bf16 v[58:61], v[156:159], v[176:179], v[58:61]
	v_mfma_f32_16x16x32_bf16 v[54:57], v[148:151], v[184:187], v[54:57]
	v_mfma_f32_16x16x32_bf16 v[50:53], v[156:159], v[184:187], v[50:53]
	v_mfma_f32_16x16x32_bf16 v[38:41], v[148:151], v[192:195], v[38:41]
	v_mfma_f32_16x16x32_bf16 v[34:37], v[156:159], v[192:195], v[34:37]
	v_mfma_f32_16x16x32_bf16 v[22:25], v[148:151], v[200:203], v[22:25]
	v_mfma_f32_16x16x32_bf16 v[18:21], v[156:159], v[200:203], v[18:21]
	s_barrier
; #define PG8_STAGE(bufoff, gbase, voff) do { _Pragma("unroll") for (int _i = 0; _i < 2; ++_i) \
;         __builtin_amdgcn_global_load_lds((const unsigned*)((const char*)(gbase) + (voff)[_i]), (LAS unsigned*)(lds + (bufoff) + ldsw + _i * 8192), 16, 0, 0); } while (0)
; #define PG8_LDA(dst, b, h) do { _Pragma("unroll") for (int m = 0; m < 4; ++m) _Pragma("unroll") for (int k = 0; k < 2; ++k) dst[m][k] = *(const LAS bf16x8*)(lds + PG8_SA(b, h) + aoff + m * 2048 + k * 1024); } while (0)
; #define PG8_LDB(dst, b, h) do { _Pragma("unroll") for (int n = 0; n < 2; ++n) _Pragma("unroll") for (int k = 0; k < 2; ++k) dst[n][k] = *(const LAS bf16x8*)(lds + PG8_SB(b, h) + boff + n * 2048 + k * 1024); } while (0)
; #define PG8_MMA(ai, bj, At, Bt) do { __builtin_amdgcn_s_setprio(1); _Pragma("unroll") for (int m = 0; m < 4; ++m) _Pragma("unroll") for (int n = 0; n < 2; ++n) _Pragma("unroll") for (int k = 0; k < 2; ++k) \
;         acc[ai][bj][m][n] = __builtin_amdgcn_mfma_f32_16x16x32_bf16(Bt[n][k], At[m][k], acc[ai][bj][m][n], 0, 0, 0); __builtin_amdgcn_s_setprio(0); } while (0)
; #define PG8_WAIT_V(n) asm volatile("s_waitcnt vmcnt(" #n ")" ::: "memory")
; #define PG8_WAIT_L(n) asm volatile("s_waitcnt lgkmcnt(" #n ")" ::: "memory")
; #define PG8_BAR __builtin_amdgcn_s_barrier()
; #define PG8_SCHED __builtin_amdgcn_sched_barrier(0)
; template <class Epi>
; DI void gemm_phase(int wv, LAS unsigned char* lds, const GemmD g, const Epi& E) {
;     ...
;             PG8_STAGE(PG8_SB(0, 1), b2 + hstepB, voffB);
;             PG8_WAIT_V(6); PG8_BAR; PG8_MMA(1, 1, At, B1); PG8_BAR;
;             PG8_LDB(B0, 1, 0); PG8_SCHED; PG8_LDA(At, 1, 0); PG8_STAGE(PG8_SA(0, 1), a2 + hstepA, voffA);
;             PG8_WAIT_L(8); PG8_BAR; PG8_WAIT_L(0); PG8_MMA(0, 0, At, B0); PG8_BAR; PG8_SCHED;
;             PG8_LDB(B1, 1, 1); PG8_STAGE(PG8_SB(1, 0), b3, voffB);
;             PG8_BAR; PG8_WAIT_L(0); PG8_MMA(0, 1, At, B1); PG8_BAR;
;             PG8_LDA(At, 1, 1); PG8_STAGE(PG8_SA(1, 0), a3, voffA);
;             PG8_BAR; PG8_WAIT_L(0); PG8_MMA(1, 0, At, B0); PG8_BAR; PG8_SCHED;
	s_add_u32 s24, s24, s36
	s_addc_u32 s25, s25, 0
	s_add_i32 s2, s2, s37
	v_lshl_add_u64 v[222:223], s[24:25], 0, v[0:1]
	s_mov_b32 m0, s2
	v_lshl_add_u64 v[224:225], s[24:25], 0, v[130:131]
	global_load_lds_dwordx4 v[222:223], off
	s_add_i32 m0, s2, 0x2000
	s_nop 0
	global_load_lds_dwordx4 v[224:225], off
	s_waitcnt vmcnt(6)
	s_barrier
	v_mfma_f32_16x16x32_bf16 v[46:49], v[204:207], v[160:163], 0
	v_mfma_f32_16x16x32_bf16 v[42:45], v[212:215], v[160:163], 0
	v_mfma_f32_16x16x32_bf16 v[30:33], v[204:207], v[180:183], 0
	v_mfma_f32_16x16x32_bf16 v[26:29], v[212:215], v[180:183], 0
	v_mfma_f32_16x16x32_bf16 v[14:17], v[204:207], v[188:191], 0
	v_mfma_f32_16x16x32_bf16 v[10:13], v[212:215], v[188:191], 0
	v_mfma_f32_16x16x32_bf16 v[6:9], v[204:207], v[196:199], 0
	v_mfma_f32_16x16x32_bf16 v[2:5], v[212:215], v[196:199], 0
	v_mfma_f32_16x16x32_bf16 v[46:49], v[208:211], v[176:179], v[46:49]
	v_mfma_f32_16x16x32_bf16 v[42:45], v[216:219], v[176:179], v[42:45]
	v_mfma_f32_16x16x32_bf16 v[30:33], v[208:211], v[184:187], v[30:33]
	v_mfma_f32_16x16x32_bf16 v[26:29], v[216:219], v[184:187], v[26:29]
	v_mfma_f32_16x16x32_bf16 v[14:17], v[208:211], v[192:195], v[14:17]
	v_mfma_f32_16x16x32_bf16 v[10:13], v[216:219], v[192:195], v[10:13]
	v_mfma_f32_16x16x32_bf16 v[6:9], v[208:211], v[200:203], v[6:9]
	v_mfma_f32_16x16x32_bf16 v[2:5], v[216:219], v[200:203], v[2:5]
	s_add_i32 s2, 0, 0x18000
	v_add_u32_e32 v156, s2, v141
	s_barrier
	ds_read_b128 v[144:147], v156
	ds_read_b128 v[148:151], v156 offset:1024
	ds_read_b128 v[152:155], v156 offset:2048
	ds_read_b128 v[156:159], v156 offset:3072
	s_add_u32 s22, s22, 0x40000
	s_addc_u32 s23, s23, 0
	s_mov_b32 m0, s82
	v_lshl_add_u64 v[204:205], s[22:23], 0, v[134:135]
	ds_read_b128 v[160:163], v143 offset:32768
	ds_read_b128 v[176:179], v143 offset:33792
	ds_read_b128 v[180:183], v143 offset:34816
	ds_read_b128 v[184:187], v143 offset:35840
	ds_read_b128 v[188:191], v143 offset:36864
	ds_read_b128 v[192:195], v143 offset:37888
	ds_read_b128 v[196:199], v143 offset:38912
	ds_read_b128 v[200:203], v143 offset:39936
	global_load_lds_dwordx4 v[204:205], off
	v_lshl_add_u64 v[204:205], s[22:23], 0, v[132:133]
	s_mov_b32 m0, s83
	s_nop 0
	global_load_lds_dwordx4 v[204:205], off
	s_waitcnt lgkmcnt(8)
	s_barrier
	s_waitcnt lgkmcnt(0)
	s_waitcnt lgkmcnt(0)
	v_mfma_f32_16x16x32_bf16 v[126:129], v[144:147], v[160:163], v[126:129]
	v_mfma_f32_16x16x32_bf16 v[122:125], v[152:155], v[160:163], v[122:125]
	v_mfma_f32_16x16x32_bf16 v[118:121], v[144:147], v[180:183], v[118:121]
	v_mfma_f32_16x16x32_bf16 v[114:117], v[152:155], v[180:183], v[114:117]
	v_mfma_f32_16x16x32_bf16 v[102:105], v[144:147], v[188:191], v[102:105]
	v_mfma_f32_16x16x32_bf16 v[98:101], v[152:155], v[188:191], v[98:101]
	v_mfma_f32_16x16x32_bf16 v[86:89], v[144:147], v[196:199], v[86:89]
	v_mfma_f32_16x16x32_bf16 v[82:85], v[152:155], v[196:199], v[82:85]
	v_mfma_f32_16x16x32_bf16 v[126:129], v[148:151], v[176:179], v[126:129]
	v_mfma_f32_16x16x32_bf16 v[122:125], v[156:159], v[176:179], v[122:125]
	v_mfma_f32_16x16x32_bf16 v[118:121], v[148:151], v[184:187], v[118:121]
	v_mfma_f32_16x16x32_bf16 v[114:117], v[156:159], v[184:187], v[114:117]
	v_mfma_f32_16x16x32_bf16 v[102:105], v[148:151], v[192:195], v[102:105]
	v_mfma_f32_16x16x32_bf16 v[98:101], v[156:159], v[192:195], v[98:101]
	v_mfma_f32_16x16x32_bf16 v[86:89], v[148:151], v[200:203], v[86:89]
	v_mfma_f32_16x16x32_bf16 v[82:85], v[156:159], v[200:203], v[82:85]
	s_barrier
	s_add_i32 s3, 0, 0x1c000
	s_add_i32 s2, s2, s37
	v_add_u32_e32 v216, s3, v141
	v_lshl_add_u64 v[164:165], v[164:165], 0, s[58:59]
	s_mov_b32 m0, s2
	ds_read_b128 v[204:207], v216
	ds_read_b128 v[208:211], v216 offset:1024
	ds_read_b128 v[212:215], v216 offset:2048
	ds_read_b128 v[216:219], v216 offset:3072
	global_load_lds_dwordx4 v[164:165], off
	v_lshl_add_u64 v[164:165], v[168:169], 0, s[58:59]
	s_add_i32 m0, s2, 0x2000
	s_nop 0
	global_load_lds_dwordx4 v[164:165], off
	s_barrier
; #define PG8_STAGE(bufoff, gbase, voff) do { _Pragma("unroll") for (int _i = 0; _i < 2; ++_i) \
;         __builtin_amdgcn_global_load_lds((const unsigned*)((const char*)(gbase) + (voff)[_i]), (LAS unsigned*)(lds + (bufoff) + ldsw + _i * 8192), 16, 0, 0); } while (0)
; #define PG8_LDA(dst, b, h) do { _Pragma("unroll") for (int m = 0; m < 4; ++m) _Pragma("unroll") for (int k = 0; k < 2; ++k) dst[m][k] = *(const LAS bf16x8*)(lds + PG8_SA(b, h) + aoff + m * 2048 + k * 1024); } while (0)
; #define PG8_LDB(dst, b, h) do { _Pragma("unroll") for (int n = 0; n < 2; ++n) _Pragma("unroll") for (int k = 0; k < 2; ++k) dst[n][k] = *(const LAS bf16x8*)(lds + PG8_SB(b, h) + boff + n * 2048 + k * 1024); } while (0)
; #define PG8_MMA(ai, bj, At, Bt) do { __builtin_amdgcn_s_setprio(1); _Pragma("unroll") for (int m = 0; m < 4; ++m) _Pragma("unroll") for (int n = 0; n < 2; ++n) _Pragma("unroll") for (int k = 0; k < 2; ++k) \
;         acc[ai][bj][m][n] = __builtin_amdgcn_mfma_f32_16x16x32_bf16(Bt[n][k], At[m][k], acc[ai][bj][m][n], 0, 0, 0); __builtin_amdgcn_s_setprio(0); } while (0)
; #define PG8_WAIT_V(n) asm volatile("s_waitcnt vmcnt(" #n ")" ::: "memory")
; #define PG8_WAIT_L(n) asm volatile("s_waitcnt lgkmcnt(" #n ")" ::: "memory")
; #define PG8_BAR __builtin_amdgcn_s_barrier()
; #define PG8_SCHED __builtin_amdgcn_sched_barrier(0)
; template <class Epi>
; DI void gemm_phase(int wv, LAS unsigned char* lds, const GemmD g, const Epi& E) {
;     ...
;             PG8_WAIT_L(8); PG8_BAR; PG8_WAIT_L(0); PG8_MMA(0, 0, At, B0); PG8_BAR; PG8_SCHED;
;             PG8_LDB(B1, 1, 1); PG8_STAGE(PG8_SB(1, 0), b3, voffB);
;             PG8_BAR; PG8_WAIT_L(0); PG8_MMA(0, 1, At, B1); PG8_BAR;
;             PG8_LDA(At, 1, 1); PG8_STAGE(PG8_SA(1, 0), a3, voffA);
;             PG8_BAR; PG8_WAIT_L(0); PG8_MMA(1, 0, At, B0); PG8_BAR; PG8_SCHED;
;             PG8_STAGE(PG8_SB(1, 1), b3 + hstepB, voffB);
;             PG8_WAIT_V(6); PG8_BAR; PG8_MMA(1, 1, At, B1); PG8_BAR;
;         }
	s_waitcnt lgkmcnt(0)
	s_waitcnt lgkmcnt(0)
	v_mfma_f32_16x16x32_bf16 v[110:113], v[204:207], v[160:163], v[110:113]
	v_mfma_f32_16x16x32_bf16 v[106:109], v[212:215], v[160:163], v[106:109]
	v_mfma_f32_16x16x32_bf16 v[94:97], v[204:207], v[180:183], v[94:97]
	v_mfma_f32_16x16x32_bf16 v[90:93], v[212:215], v[180:183], v[90:93]
	v_mfma_f32_16x16x32_bf16 v[78:81], v[204:207], v[188:191], v[78:81]
	v_mfma_f32_16x16x32_bf16 v[74:77], v[212:215], v[188:191], v[74:77]
	v_mfma_f32_16x16x32_bf16 v[70:73], v[204:207], v[196:199], v[70:73]
	v_mfma_f32_16x16x32_bf16 v[66:69], v[212:215], v[196:199], v[66:69]
	v_mfma_f32_16x16x32_bf16 v[110:113], v[208:211], v[176:179], v[110:113]
	v_mfma_f32_16x16x32_bf16 v[106:109], v[216:219], v[176:179], v[106:109]
	v_mfma_f32_16x16x32_bf16 v[94:97], v[208:211], v[184:187], v[94:97]
	v_mfma_f32_16x16x32_bf16 v[90:93], v[216:219], v[184:187], v[90:93]
	v_mfma_f32_16x16x32_bf16 v[78:81], v[208:211], v[192:195], v[78:81]
	v_mfma_f32_16x16x32_bf16 v[74:77], v[216:219], v[192:195], v[74:77]
	v_mfma_f32_16x16x32_bf16 v[70:73], v[208:211], v[200:203], v[70:73]
	v_mfma_f32_16x16x32_bf16 v[66:69], v[216:219], v[200:203], v[66:69]
	s_mov_b32 m0, s84
	v_lshl_add_u64 v[164:165], v[170:171], 0, s[58:59]
	s_barrier
	ds_read_b128 v[160:163], v143 offset:49152
	ds_read_b128 v[176:179], v143 offset:50176
	ds_read_b128 v[180:183], v143 offset:51200
	ds_read_b128 v[184:187], v143 offset:52224
	ds_read_b128 v[188:191], v143 offset:53248
	ds_read_b128 v[192:195], v143 offset:54272
	ds_read_b128 v[196:199], v143 offset:55296
	ds_read_b128 v[200:203], v143 offset:56320
	global_load_lds_dwordx4 v[164:165], off
	v_lshl_add_u64 v[164:165], v[220:221], 0, s[58:59]
	s_mov_b32 m0, s85
	s_nop 0
	global_load_lds_dwordx4 v[164:165], off
	s_barrier
	s_waitcnt lgkmcnt(0)
	s_waitcnt lgkmcnt(0)
	v_mfma_f32_16x16x32_bf16 v[62:65], v[144:147], v[160:163], v[62:65]
	v_mfma_f32_16x16x32_bf16 v[58:61], v[152:155], v[160:163], v[58:61]
	v_mfma_f32_16x16x32_bf16 v[54:57], v[144:147], v[180:183], v[54:57]
	v_mfma_f32_16x16x32_bf16 v[50:53], v[152:155], v[180:183], v[50:53]
	v_mfma_f32_16x16x32_bf16 v[38:41], v[144:147], v[188:191], v[38:41]
	v_mfma_f32_16x16x32_bf16 v[34:37], v[152:155], v[188:191], v[34:37]
	v_mfma_f32_16x16x32_bf16 v[22:25], v[144:147], v[196:199], v[22:25]
	v_mfma_f32_16x16x32_bf16 v[18:21], v[152:155], v[196:199], v[18:21]
	v_mfma_f32_16x16x32_bf16 v[62:65], v[148:151], v[176:179], v[62:65]
	v_mfma_f32_16x16x32_bf16 v[58:61], v[156:159], v[176:179], v[58:61]
	v_mfma_f32_16x16x32_bf16 v[54:57], v[148:151], v[184:187], v[54:57]
	v_mfma_f32_16x16x32_bf16 v[50:53], v[156:159], v[184:187], v[50:53]
	v_mfma_f32_16x16x32_bf16 v[38:41], v[148:151], v[192:195], v[38:41]
	v_mfma_f32_16x16x32_bf16 v[34:37], v[156:159], v[192:195], v[34:37]
	v_mfma_f32_16x16x32_bf16 v[22:25], v[148:151], v[200:203], v[22:25]
	v_mfma_f32_16x16x32_bf16 v[18:21], v[156:159], v[200:203], v[18:21]
	s_barrier
	s_add_i32 s2, s3, s37
	v_lshl_add_u64 v[144:145], v[222:223], 0, s[58:59]
	s_mov_b32 m0, s2
	s_nop 0
	global_load_lds_dwordx4 v[144:145], off
	v_lshl_add_u64 v[144:145], v[224:225], 0, s[58:59]
	s_add_i32 m0, s2, 0x2000
	s_nop 0
	global_load_lds_dwordx4 v[144:145], off
	s_waitcnt vmcnt(6)
	s_barrier
	v_mfma_f32_16x16x32_bf16 v[46:49], v[204:207], v[160:163], v[46:49]
	v_mfma_f32_16x16x32_bf16 v[42:45], v[212:215], v[160:163], v[42:45]
	v_mfma_f32_16x16x32_bf16 v[30:33], v[204:207], v[180:183], v[30:33]
	v_mfma_f32_16x16x32_bf16 v[26:29], v[212:215], v[180:183], v[26:29]
	v_mfma_f32_16x16x32_bf16 v[14:17], v[204:207], v[188:191], v[14:17]
	v_mfma_f32_16x16x32_bf16 v[10:13], v[212:215], v[188:191], v[10:13]
	v_mfma_f32_16x16x32_bf16 v[6:9], v[204:207], v[196:199], v[6:9]
	v_mfma_f32_16x16x32_bf16 v[2:5], v[212:215], v[196:199], v[2:5]
	v_mfma_f32_16x16x32_bf16 v[46:49], v[208:211], v[176:179], v[46:49]
	v_mfma_f32_16x16x32_bf16 v[42:45], v[216:219], v[176:179], v[42:45]
	v_mfma_f32_16x16x32_bf16 v[30:33], v[208:211], v[184:187], v[30:33]
	v_mfma_f32_16x16x32_bf16 v[26:29], v[216:219], v[184:187], v[26:29]
	v_mfma_f32_16x16x32_bf16 v[14:17], v[208:211], v[192:195], v[14:17]
	v_mfma_f32_16x16x32_bf16 v[10:13], v[216:219], v[192:195], v[10:13]
	v_mfma_f32_16x16x32_bf16 v[6:9], v[208:211], v[200:203], v[6:9]
	v_mfma_f32_16x16x32_bf16 v[2:5], v[216:219], v[200:203], v[2:5]
	s_add_i32 s95, s95, 2
	s_add_u32 s4, s4, 0x100
	s_addc_u32 s5, s5, 0
	s_add_u32 vcc_hi, vcc_hi, 0x100
	s_addc_u32 s75, s75, 0
	s_cmp_gt_u32 s95, 13
	s_barrier
	s_cbranch_scc0 .LBB0_99
	s_branch .Lgemm_epi_a
	.p2align 6

; #define PG8_STAGE(bufoff, gbase, voff) do { _Pragma("unroll") for (int _i = 0; _i < 2; ++_i) \
;         __builtin_amdgcn_global_load_lds((const unsigned*)((const char*)(gbase) + (voff)[_i]), (LAS unsigned*)(lds + (bufoff) + ldsw + _i * 8192), 16, 0, 0); } while (0)
; #define PG8_LDA(dst, b, h) do { _Pragma("unroll") for (int m = 0; m < 4; ++m) _Pragma("unroll") for (int k = 0; k < 2; ++k) dst[m][k] = *(const LAS bf16x8*)(lds + PG8_SA(b, h) + aoff + m * 2048 + k * 1024); } while (0)
; #define PG8_LDB(dst, b, h) do { _Pragma("unroll") for (int n = 0; n < 2; ++n) _Pragma("unroll") for (int k = 0; k < 2; ++k) dst[n][k] = *(const LAS bf16x8*)(lds + PG8_SB(b, h) + boff + n * 2048 + k * 1024); } while (0)
; #define PG8_MMA(ai, bj, At, Bt) do { __builtin_amdgcn_s_setprio(1); _Pragma("unroll") for (int m = 0; m < 4; ++m) _Pragma("unroll") for (int n = 0; n < 2; ++n) _Pragma("unroll") for (int k = 0; k < 2; ++k) \
;         acc[ai][bj][m][n] = __builtin_amdgcn_mfma_f32_16x16x32_bf16(Bt[n][k], At[m][k], acc[ai][bj][m][n], 0, 0, 0); __builtin_amdgcn_s_setprio(0); } while (0)
; #define PG8_WAIT_L(n) asm volatile("s_waitcnt lgkmcnt(" #n ")" ::: "memory")
; template <class Epi>
; DI void gemm_phase(int wv, LAS unsigned char* lds, const GemmD g, const Epi& E) {
;     ...
;         const bool has_next = S.next(ui + 1, nxt);
;         const char* nA = has_next ? (const char*)g.A + (size_t)nxt.pm * 256 * g.lda * 2 : cA; const char* nB = has_next ? (const char*)g.Bt + PG8_BROW(nxt.pn) * (size_t)g.ldb * 2 : cB;
;         for (int t = 0; t < nt; t += 2) {
;             const bool last = (t == nt - 2);
;             const char* a1 = cA + (size_t)(t + 1) * kstep;
;             const char* a2 = last ? nA : cA + (size_t)(t + 2) * kstep; const char* b2 = last ? nB : cB + (size_t)(t + 2) * kstep;
;             const char* a3 = a2 + kstep; const char* b3 = b2 + kstep;
;             PG8_LDB(B0, 0, 0); PG8_SCHED; PG8_LDA(At, 0, 0); PG8_STAGE(PG8_SA(1, 1), a1 + hstepA, voffA);
;             PG8_WAIT_L(8); PG8_BAR; PG8_WAIT_L(0); PG8_MMA(0, 0, At, B0); PG8_BAR; PG8_SCHED;
;             PG8_LDB(B1, 0, 1); PG8_STAGE(PG8_SB(0, 0), b2, voffB);
;             PG8_BAR; PG8_WAIT_L(0); PG8_MMA(0, 1, At, B1); PG8_BAR;
;             PG8_LDA(At, 0, 1); PG8_STAGE(PG8_SA(0, 0), a2, voffA);
;             PG8_BAR; PG8_WAIT_L(0); PG8_MMA(1, 0, At, B0); PG8_BAR; PG8_SCHED;
.LBB0_489:
	s_ashr_i32 s7, s6, 31
	v_cmp_lt_i64_e32 vcc, s[8:9], v[228:229]
	s_lshl_b64 s[8:9], s[6:7], 19
	s_add_u32 s8, s76, s8
	s_addc_u32 s9, s78, s9
	s_and_b64 s[16:17], vcc, exec
	s_cselect_b32 s7, s9, s27
	s_cselect_b32 s13, s8, s26
	s_lshl_b32 s16, s86, 8
	s_ashr_i32 s17, s16, 31
	s_lshl_b64 s[16:17], s[16:17], 11
	s_add_u32 s22, s39, s16
	s_addc_u32 s23, s40, s17
	s_and_b64 s[16:17], vcc, exec
	s_cselect_b32 s16, s23, s29
	s_cselect_b32 s17, s22, s28
	s_add_u32 s26, s26, 0x40080
	s_addc_u32 s27, s27, 0
	s_add_u32 s36, s28, 0x100
	s_addc_u32 s38, s29, 0
	s_mov_b32 s41, -2
	s_add_u32 s2, s26, 0xfffc0080
	s_addc_u32 s3, s27, -1
	s_add_i32 s18, 0, 0x10000
	v_add_u32_e32 v140, s18, v144
	ds_read_b128 v[148:151], v140
	ds_read_b128 v[152:155], v140 offset:1024
	ds_read_b128 v[156:159], v140 offset:2048
	ds_read_b128 v[160:163], v140 offset:3072
	s_cmp_eq_u32 s41, 12
	s_cselect_b32 s31, s7, s3
	s_cselect_b32 s30, s13, s2
	s_cselect_b32 s29, s16, s38
	s_cselect_b32 s28, s17, s36
	v_lshl_add_u64 v[140:141], s[26:27], 0, v[136:137]
	s_add_i32 m0, s25, 0xc000
	ds_read_b128 v[168:171], v146
	ds_read_b128 v[176:179], v146 offset:1024
	ds_read_b128 v[180:183], v146 offset:2048
	ds_read_b128 v[184:187], v146 offset:3072
	ds_read_b128 v[188:191], v146 offset:4096
	ds_read_b128 v[192:195], v146 offset:5120
	ds_read_b128 v[196:199], v146 offset:6144
	ds_read_b128 v[200:203], v146 offset:7168
	global_load_lds_dwordx4 v[140:141], off
	v_lshl_add_u64 v[140:141], s[26:27], 0, v[138:139]
	s_add_i32 m0, s25, 0xe000
	s_nop 0
	global_load_lds_dwordx4 v[140:141], off
	s_waitcnt lgkmcnt(8)
	s_barrier
	s_waitcnt lgkmcnt(0)
	s_waitcnt lgkmcnt(0)
	v_mfma_f32_16x16x32_bf16 v[126:129], v[148:151], v[168:171], 0
	v_mfma_f32_16x16x32_bf16 v[122:125], v[156:159], v[168:171], 0
	v_mfma_f32_16x16x32_bf16 v[110:113], v[148:151], v[180:183], 0
	v_mfma_f32_16x16x32_bf16 v[106:109], v[156:159], v[180:183], 0
	v_mfma_f32_16x16x32_bf16 v[94:97], v[148:151], v[188:191], 0
	v_mfma_f32_16x16x32_bf16 v[90:93], v[156:159], v[188:191], 0
	v_mfma_f32_16x16x32_bf16 v[78:81], v[148:151], v[196:199], 0
	v_mfma_f32_16x16x32_bf16 v[74:77], v[156:159], v[196:199], 0
	v_mfma_f32_16x16x32_bf16 v[126:129], v[152:155], v[176:179], v[126:129]
	v_mfma_f32_16x16x32_bf16 v[122:125], v[160:163], v[176:179], v[122:125]
	v_mfma_f32_16x16x32_bf16 v[110:113], v[152:155], v[184:187], v[110:113]
	v_mfma_f32_16x16x32_bf16 v[106:109], v[160:163], v[184:187], v[106:109]
	v_mfma_f32_16x16x32_bf16 v[94:97], v[152:155], v[192:195], v[94:97]
	v_mfma_f32_16x16x32_bf16 v[90:93], v[160:163], v[192:195], v[90:93]
	v_mfma_f32_16x16x32_bf16 v[78:81], v[152:155], v[200:203], v[78:81]
	v_mfma_f32_16x16x32_bf16 v[74:77], v[160:163], v[200:203], v[74:77]
	s_barrier
	s_add_i32 s2, 0, 0x14000
	v_add_u32_e32 v140, s2, v144
	s_add_i32 s3, s18, s79
	ds_read_b128 v[204:207], v140
	ds_read_b128 v[208:211], v140 offset:1024
	ds_read_b128 v[212:215], v140 offset:2048
	ds_read_b128 v[216:219], v140 offset:3072
	v_lshl_add_u64 v[140:141], s[28:29], 0, v[0:1]
	s_mov_b32 m0, s3
	v_lshl_add_u64 v[164:165], s[28:29], 0, v[134:135]
	global_load_lds_dwordx4 v[140:141], off
	s_add_i32 m0, s3, 0x2000
	s_nop 0
	global_load_lds_dwordx4 v[164:165], off
	s_barrier
	s_waitcnt lgkmcnt(0)
	s_waitcnt lgkmcnt(0)
	v_mfma_f32_16x16x32_bf16 v[118:121], v[204:207], v[168:171], 0
	v_mfma_f32_16x16x32_bf16 v[114:117], v[212:215], v[168:171], 0
	v_mfma_f32_16x16x32_bf16 v[102:105], v[204:207], v[180:183], 0
	v_mfma_f32_16x16x32_bf16 v[98:101], v[212:215], v[180:183], 0
	v_mfma_f32_16x16x32_bf16 v[86:89], v[204:207], v[188:191], 0
	v_mfma_f32_16x16x32_bf16 v[82:85], v[212:215], v[188:191], 0
	v_mfma_f32_16x16x32_bf16 v[70:73], v[204:207], v[196:199], 0
	v_mfma_f32_16x16x32_bf16 v[66:69], v[212:215], v[196:199], 0
	v_mfma_f32_16x16x32_bf16 v[118:121], v[208:211], v[176:179], v[118:121]
	v_mfma_f32_16x16x32_bf16 v[114:117], v[216:219], v[176:179], v[114:117]
	v_mfma_f32_16x16x32_bf16 v[102:105], v[208:211], v[184:187], v[102:105]
	v_mfma_f32_16x16x32_bf16 v[98:101], v[216:219], v[184:187], v[98:101]
	v_mfma_f32_16x16x32_bf16 v[86:89], v[208:211], v[192:195], v[86:89]
	v_mfma_f32_16x16x32_bf16 v[82:85], v[216:219], v[192:195], v[82:85]
	v_mfma_f32_16x16x32_bf16 v[70:73], v[208:211], v[200:203], v[70:73]
	v_mfma_f32_16x16x32_bf16 v[66:69], v[216:219], v[200:203], v[66:69]
	s_mov_b32 m0, s25
	v_lshl_add_u64 v[220:221], s[30:31], 0, v[130:131]
	s_barrier
	ds_read_b128 v[168:171], v146 offset:16384
	ds_read_b128 v[176:179], v146 offset:17408
	ds_read_b128 v[180:183], v146 offset:18432
	ds_read_b128 v[184:187], v146 offset:19456
	ds_read_b128 v[188:191], v146 offset:20480
	ds_read_b128 v[192:195], v146 offset:21504
	ds_read_b128 v[196:199], v146 offset:22528
	ds_read_b128 v[200:203], v146 offset:23552
	global_load_lds_dwordx4 v[220:221], off
	v_lshl_add_u64 v[222:223], s[30:31], 0, v[132:133]
	s_mov_b32 m0, s80
	s_nop 0
	global_load_lds_dwordx4 v[222:223], off
	s_barrier
	s_waitcnt lgkmcnt(0)
	s_waitcnt lgkmcnt(0)
	v_mfma_f32_16x16x32_bf16 v[62:65], v[148:151], v[168:171], 0
	v_mfma_f32_16x16x32_bf16 v[58:61], v[156:159], v[168:171], 0
	v_mfma_f32_16x16x32_bf16 v[46:49], v[148:151], v[180:183], 0
	v_mfma_f32_16x16x32_bf16 v[42:45], v[156:159], v[180:183], 0
	v_mfma_f32_16x16x32_bf16 v[30:33], v[148:151], v[188:191], 0
	v_mfma_f32_16x16x32_bf16 v[26:29], v[156:159], v[188:191], 0
	v_mfma_f32_16x16x32_bf16 v[14:17], v[148:151], v[196:199], 0
	v_mfma_f32_16x16x32_bf16 v[10:13], v[156:159], v[196:199], 0
	v_mfma_f32_16x16x32_bf16 v[62:65], v[152:155], v[176:179], v[62:65]
	v_mfma_f32_16x16x32_bf16 v[58:61], v[160:163], v[176:179], v[58:61]
	v_mfma_f32_16x16x32_bf16 v[46:49], v[152:155], v[184:187], v[46:49]
	v_mfma_f32_16x16x32_bf16 v[42:45], v[160:163], v[184:187], v[42:45]
	v_mfma_f32_16x16x32_bf16 v[30:33], v[152:155], v[192:195], v[30:33]
	v_mfma_f32_16x16x32_bf16 v[26:29], v[160:163], v[192:195], v[26:29]
	v_mfma_f32_16x16x32_bf16 v[14:17], v[152:155], v[200:203], v[14:17]
	v_mfma_f32_16x16x32_bf16 v[10:13], v[160:163], v[200:203], v[10:13]
	s_barrier
; #define PG8_STAGE(bufoff, gbase, voff) do { _Pragma("unroll") for (int _i = 0; _i < 2; ++_i) \
;         __builtin_amdgcn_global_load_lds((const unsigned*)((const char*)(gbase) + (voff)[_i]), (LAS unsigned*)(lds + (bufoff) + ldsw + _i * 8192), 16, 0, 0); } while (0)
; #define PG8_LDA(dst, b, h) do { _Pragma("unroll") for (int m = 0; m < 4; ++m) _Pragma("unroll") for (int k = 0; k < 2; ++k) dst[m][k] = *(const LAS bf16x8*)(lds + PG8_SA(b, h) + aoff + m * 2048 + k * 1024); } while (0)
; #define PG8_LDB(dst, b, h) do { _Pragma("unroll") for (int n = 0; n < 2; ++n) _Pragma("unroll") for (int k = 0; k < 2; ++k) dst[n][k] = *(const LAS bf16x8*)(lds + PG8_SB(b, h) + boff + n * 2048 + k * 1024); } while (0)
; #define PG8_MMA(ai, bj, At, Bt) do { __builtin_amdgcn_s_setprio(1); _Pragma("unroll") for (int m = 0; m < 4; ++m) _Pragma("unroll") for (int n = 0; n < 2; ++n) _Pragma("unroll") for (int k = 0; k < 2; ++k) \
;         acc[ai][bj][m][n] = __builtin_amdgcn_mfma_f32_16x16x32_bf16(Bt[n][k], At[m][k], acc[ai][bj][m][n], 0, 0, 0); __builtin_amdgcn_s_setprio(0); } while (0)
; #define PG8_WAIT_V(n) asm volatile("s_waitcnt vmcnt(" #n ")" ::: "memory")
; #define PG8_WAIT_L(n) asm volatile("s_waitcnt lgkmcnt(" #n ")" ::: "memory")
; #define PG8_BAR __builtin_amdgcn_s_barrier()
; #define PG8_SCHED __builtin_amdgcn_sched_barrier(0)
; template <class Epi>
; DI void gemm_phase(int wv, LAS unsigned char* lds, const GemmD g, const Epi& E) {
;     ...
;             PG8_STAGE(PG8_SB(0, 1), b2 + hstepB, voffB);
;             PG8_WAIT_V(6); PG8_BAR; PG8_MMA(1, 1, At, B1); PG8_BAR;
;             PG8_LDB(B0, 1, 0); PG8_SCHED; PG8_LDA(At, 1, 0); PG8_STAGE(PG8_SA(0, 1), a2 + hstepA, voffA);
;             PG8_WAIT_L(8); PG8_BAR; PG8_WAIT_L(0); PG8_MMA(0, 0, At, B0); PG8_BAR; PG8_SCHED;
;             PG8_LDB(B1, 1, 1); PG8_STAGE(PG8_SB(1, 0), b3, voffB);
	s_add_u32 s18, s28, 0x40000
	s_addc_u32 s19, s29, 0
	s_add_i32 s2, s2, s79
	v_lshl_add_u64 v[148:149], s[18:19], 0, v[0:1]
	s_mov_b32 m0, s2
	s_nop 0
	global_load_lds_dwordx4 v[148:149], off
	v_lshl_add_u64 v[148:149], s[18:19], 0, v[134:135]
	s_add_i32 m0, s2, 0x2000
	s_nop 0
	global_load_lds_dwordx4 v[148:149], off
	s_waitcnt vmcnt(6)
	s_barrier
	v_mfma_f32_16x16x32_bf16 v[54:57], v[204:207], v[168:171], 0
	v_mfma_f32_16x16x32_bf16 v[50:53], v[212:215], v[168:171], 0
	v_mfma_f32_16x16x32_bf16 v[38:41], v[204:207], v[180:183], 0
	v_mfma_f32_16x16x32_bf16 v[34:37], v[212:215], v[180:183], 0
	v_mfma_f32_16x16x32_bf16 v[22:25], v[204:207], v[188:191], 0
	v_mfma_f32_16x16x32_bf16 v[18:21], v[212:215], v[188:191], 0
	v_mfma_f32_16x16x32_bf16 v[6:9], v[204:207], v[196:199], 0
	v_mfma_f32_16x16x32_bf16 v[2:5], v[212:215], v[196:199], 0
	v_mfma_f32_16x16x32_bf16 v[54:57], v[208:211], v[176:179], v[54:57]
	v_mfma_f32_16x16x32_bf16 v[50:53], v[216:219], v[176:179], v[50:53]
	v_mfma_f32_16x16x32_bf16 v[38:41], v[208:211], v[184:187], v[38:41]
	v_mfma_f32_16x16x32_bf16 v[34:37], v[216:219], v[184:187], v[34:37]
	v_mfma_f32_16x16x32_bf16 v[22:25], v[208:211], v[192:195], v[22:25]
	v_mfma_f32_16x16x32_bf16 v[18:21], v[216:219], v[192:195], v[18:21]
	v_mfma_f32_16x16x32_bf16 v[6:9], v[208:211], v[200:203], v[6:9]
	v_mfma_f32_16x16x32_bf16 v[2:5], v[216:219], v[200:203], v[2:5]
	s_add_i32 s2, 0, 0x18000
	v_add_u32_e32 v147, s2, v144
	s_barrier
	ds_read_b128 v[148:151], v147
	ds_read_b128 v[152:155], v147 offset:1024
	ds_read_b128 v[156:159], v147 offset:2048
	ds_read_b128 v[160:163], v147 offset:3072
	s_add_u32 s18, s30, 0x40000
	s_addc_u32 s19, s31, 0
	s_mov_b32 m0, s81
	v_lshl_add_u64 v[204:205], s[18:19], 0, v[130:131]
	ds_read_b128 v[168:171], v146 offset:32768
	ds_read_b128 v[176:179], v146 offset:33792
	ds_read_b128 v[180:183], v146 offset:34816
	ds_read_b128 v[184:187], v146 offset:35840
	ds_read_b128 v[188:191], v146 offset:36864
	ds_read_b128 v[192:195], v146 offset:37888
	ds_read_b128 v[196:199], v146 offset:38912
	ds_read_b128 v[200:203], v146 offset:39936
	global_load_lds_dwordx4 v[204:205], off
	v_lshl_add_u64 v[204:205], s[18:19], 0, v[132:133]
	s_mov_b32 m0, s82
	s_nop 0
	global_load_lds_dwordx4 v[204:205], off
	s_waitcnt lgkmcnt(8)
	s_barrier
	s_waitcnt lgkmcnt(0)
	s_waitcnt lgkmcnt(0)
	v_mfma_f32_16x16x32_bf16 v[126:129], v[148:151], v[168:171], v[126:129]
	v_mfma_f32_16x16x32_bf16 v[122:125], v[156:159], v[168:171], v[122:125]
	v_mfma_f32_16x16x32_bf16 v[110:113], v[148:151], v[180:183], v[110:113]
	v_mfma_f32_16x16x32_bf16 v[106:109], v[156:159], v[180:183], v[106:109]
	v_mfma_f32_16x16x32_bf16 v[94:97], v[148:151], v[188:191], v[94:97]
	v_mfma_f32_16x16x32_bf16 v[90:93], v[156:159], v[188:191], v[90:93]
	v_mfma_f32_16x16x32_bf16 v[78:81], v[148:151], v[196:199], v[78:81]
	v_mfma_f32_16x16x32_bf16 v[74:77], v[156:159], v[196:199], v[74:77]
	v_mfma_f32_16x16x32_bf16 v[126:129], v[152:155], v[176:179], v[126:129]
	v_mfma_f32_16x16x32_bf16 v[122:125], v[160:163], v[176:179], v[122:125]
	v_mfma_f32_16x16x32_bf16 v[110:113], v[152:155], v[184:187], v[110:113]
	v_mfma_f32_16x16x32_bf16 v[106:109], v[160:163], v[184:187], v[106:109]
	v_mfma_f32_16x16x32_bf16 v[94:97], v[152:155], v[192:195], v[94:97]
	v_mfma_f32_16x16x32_bf16 v[90:93], v[160:163], v[192:195], v[90:93]
	v_mfma_f32_16x16x32_bf16 v[78:81], v[152:155], v[200:203], v[78:81]
	v_mfma_f32_16x16x32_bf16 v[74:77], v[160:163], v[200:203], v[74:77]
	s_barrier
	s_add_i32 s3, 0, 0x1c000
	s_add_i32 s2, s2, s79
	v_add_u32_e32 v147, s3, v144
	v_lshl_add_u64 v[140:141], v[140:141], 0, s[58:59]
	s_mov_b32 m0, s2
	ds_read_b128 v[204:207], v147
	ds_read_b128 v[208:211], v147 offset:1024
	ds_read_b128 v[212:215], v147 offset:2048
	ds_read_b128 v[216:219], v147 offset:3072
	global_load_lds_dwordx4 v[140:141], off
	v_lshl_add_u64 v[140:141], v[164:165], 0, s[58:59]
	s_add_i32 m0, s2, 0x2000
	s_nop 0
	global_load_lds_dwordx4 v[140:141], off
	s_barrier
; #define PG8_STAGE(bufoff, gbase, voff) do { _Pragma("unroll") for (int _i = 0; _i < 2; ++_i) \
;         __builtin_amdgcn_global_load_lds((const unsigned*)((const char*)(gbase) + (voff)[_i]), (LAS unsigned*)(lds + (bufoff) + ldsw + _i * 8192), 16, 0, 0); } while (0)
; #define PG8_LDA(dst, b, h) do { _Pragma("unroll") for (int m = 0; m < 4; ++m) _Pragma("unroll") for (int k = 0; k < 2; ++k) dst[m][k] = *(const LAS bf16x8*)(lds + PG8_SA(b, h) + aoff + m * 2048 + k * 1024); } while (0)
; #define PG8_MMA(ai, bj, At, Bt) do { __builtin_amdgcn_s_setprio(1); _Pragma("unroll") for (int m = 0; m < 4; ++m) _Pragma("unroll") for (int n = 0; n < 2; ++n) _Pragma("unroll") for (int k = 0; k < 2; ++k) \
;         acc[ai][bj][m][n] = __builtin_amdgcn_mfma_f32_16x16x32_bf16(Bt[n][k], At[m][k], acc[ai][bj][m][n], 0, 0, 0); __builtin_amdgcn_s_setprio(0); } while (0)
; #define PG8_WAIT_V(n) asm volatile("s_waitcnt vmcnt(" #n ")" ::: "memory")
; #define PG8_WAIT_L(n) asm volatile("s_waitcnt lgkmcnt(" #n ")" ::: "memory")
; #define PG8_BAR __builtin_amdgcn_s_barrier()
; #define PG8_SCHED __builtin_amdgcn_sched_barrier(0)
; template <class Epi>
; DI void gemm_phase(int wv, LAS unsigned char* lds, const GemmD g, const Epi& E) {
;     ...
;             PG8_BAR; PG8_WAIT_L(0); PG8_MMA(0, 1, At, B1); PG8_BAR;
;             PG8_LDA(At, 1, 1); PG8_STAGE(PG8_SA(1, 0), a3, voffA);
;             PG8_BAR; PG8_WAIT_L(0); PG8_MMA(1, 0, At, B0); PG8_BAR; PG8_SCHED;
;             PG8_STAGE(PG8_SB(1, 1), b3 + hstepB, voffB);
;             PG8_WAIT_V(6); PG8_BAR; PG8_MMA(1, 1, At, B1); PG8_BAR;
;         }
	s_waitcnt lgkmcnt(0)
	s_waitcnt lgkmcnt(0)
	v_mfma_f32_16x16x32_bf16 v[118:121], v[204:207], v[168:171], v[118:121]
	v_mfma_f32_16x16x32_bf16 v[114:117], v[212:215], v[168:171], v[114:117]
	v_mfma_f32_16x16x32_bf16 v[102:105], v[204:207], v[180:183], v[102:105]
	v_mfma_f32_16x16x32_bf16 v[98:101], v[212:215], v[180:183], v[98:101]
	v_mfma_f32_16x16x32_bf16 v[86:89], v[204:207], v[188:191], v[86:89]
	v_mfma_f32_16x16x32_bf16 v[82:85], v[212:215], v[188:191], v[82:85]
	v_mfma_f32_16x16x32_bf16 v[70:73], v[204:207], v[196:199], v[70:73]
	v_mfma_f32_16x16x32_bf16 v[66:69], v[212:215], v[196:199], v[66:69]
	v_mfma_f32_16x16x32_bf16 v[118:121], v[208:211], v[176:179], v[118:121]
	v_mfma_f32_16x16x32_bf16 v[114:117], v[216:219], v[176:179], v[114:117]
	v_mfma_f32_16x16x32_bf16 v[102:105], v[208:211], v[184:187], v[102:105]
	v_mfma_f32_16x16x32_bf16 v[98:101], v[216:219], v[184:187], v[98:101]
	v_mfma_f32_16x16x32_bf16 v[86:89], v[208:211], v[192:195], v[86:89]
	v_mfma_f32_16x16x32_bf16 v[82:85], v[216:219], v[192:195], v[82:85]
	v_mfma_f32_16x16x32_bf16 v[70:73], v[208:211], v[200:203], v[70:73]
	v_mfma_f32_16x16x32_bf16 v[66:69], v[216:219], v[200:203], v[66:69]
	s_mov_b32 m0, s83
	v_lshl_add_u64 v[140:141], v[220:221], 0, s[58:59]
	s_barrier
	ds_read_b128 v[168:171], v146 offset:49152
	ds_read_b128 v[176:179], v146 offset:50176
	ds_read_b128 v[180:183], v146 offset:51200
	ds_read_b128 v[184:187], v146 offset:52224
	ds_read_b128 v[188:191], v146 offset:53248
	ds_read_b128 v[192:195], v146 offset:54272
	ds_read_b128 v[196:199], v146 offset:55296
	ds_read_b128 v[200:203], v146 offset:56320
	global_load_lds_dwordx4 v[140:141], off
	v_lshl_add_u64 v[140:141], v[222:223], 0, s[58:59]
	s_mov_b32 m0, s84
	s_nop 0
	global_load_lds_dwordx4 v[140:141], off
	s_barrier
	s_waitcnt lgkmcnt(0)
	s_waitcnt lgkmcnt(0)
	v_mfma_f32_16x16x32_bf16 v[62:65], v[148:151], v[168:171], v[62:65]
	v_mfma_f32_16x16x32_bf16 v[58:61], v[156:159], v[168:171], v[58:61]
	v_mfma_f32_16x16x32_bf16 v[46:49], v[148:151], v[180:183], v[46:49]
	v_mfma_f32_16x16x32_bf16 v[42:45], v[156:159], v[180:183], v[42:45]
	v_mfma_f32_16x16x32_bf16 v[30:33], v[148:151], v[188:191], v[30:33]
	v_mfma_f32_16x16x32_bf16 v[26:29], v[156:159], v[188:191], v[26:29]
	v_mfma_f32_16x16x32_bf16 v[14:17], v[148:151], v[196:199], v[14:17]
	v_mfma_f32_16x16x32_bf16 v[10:13], v[156:159], v[196:199], v[10:13]
	v_mfma_f32_16x16x32_bf16 v[62:65], v[152:155], v[176:179], v[62:65]
	v_mfma_f32_16x16x32_bf16 v[58:61], v[160:163], v[176:179], v[58:61]
	v_mfma_f32_16x16x32_bf16 v[46:49], v[152:155], v[184:187], v[46:49]
	v_mfma_f32_16x16x32_bf16 v[42:45], v[160:163], v[184:187], v[42:45]
	v_mfma_f32_16x16x32_bf16 v[30:33], v[152:155], v[192:195], v[30:33]
	v_mfma_f32_16x16x32_bf16 v[26:29], v[160:163], v[192:195], v[26:29]
	v_mfma_f32_16x16x32_bf16 v[14:17], v[152:155], v[200:203], v[14:17]
	v_mfma_f32_16x16x32_bf16 v[10:13], v[160:163], v[200:203], v[10:13]
	s_barrier
	s_add_u32 s18, s28, 0x40080
	s_addc_u32 s19, s29, 0
	s_add_i32 s2, s3, s79
	v_lshl_add_u64 v[140:141], s[18:19], 0, v[0:1]
	s_mov_b32 m0, s2
	s_nop 0
	global_load_lds_dwordx4 v[140:141], off
	v_lshl_add_u64 v[140:141], s[18:19], 0, v[134:135]
	s_add_i32 m0, s2, 0x2000
	s_nop 0
	global_load_lds_dwordx4 v[140:141], off
	s_waitcnt vmcnt(6)
	s_barrier
	v_mfma_f32_16x16x32_bf16 v[54:57], v[204:207], v[168:171], v[54:57]
	v_mfma_f32_16x16x32_bf16 v[50:53], v[212:215], v[168:171], v[50:53]
	v_mfma_f32_16x16x32_bf16 v[38:41], v[204:207], v[180:183], v[38:41]
	v_mfma_f32_16x16x32_bf16 v[34:37], v[212:215], v[180:183], v[34:37]
	v_mfma_f32_16x16x32_bf16 v[22:25], v[204:207], v[188:191], v[22:25]
	v_mfma_f32_16x16x32_bf16 v[18:21], v[212:215], v[188:191], v[18:21]
	v_mfma_f32_16x16x32_bf16 v[6:9], v[204:207], v[196:199], v[6:9]
	v_mfma_f32_16x16x32_bf16 v[2:5], v[212:215], v[196:199], v[2:5]
	v_mfma_f32_16x16x32_bf16 v[54:57], v[208:211], v[176:179], v[54:57]
	v_mfma_f32_16x16x32_bf16 v[50:53], v[216:219], v[176:179], v[50:53]
	v_mfma_f32_16x16x32_bf16 v[38:41], v[208:211], v[184:187], v[38:41]
	v_mfma_f32_16x16x32_bf16 v[34:37], v[216:219], v[184:187], v[34:37]
	v_mfma_f32_16x16x32_bf16 v[22:25], v[208:211], v[192:195], v[22:25]
	v_mfma_f32_16x16x32_bf16 v[18:21], v[216:219], v[192:195], v[18:21]
	v_mfma_f32_16x16x32_bf16 v[6:9], v[208:211], v[200:203], v[6:9]
	v_mfma_f32_16x16x32_bf16 v[2:5], v[216:219], v[200:203], v[2:5]
	s_add_i32 s41, s41, 2
	s_add_u32 s26, s26, 0x100
	s_addc_u32 s27, s27, 0
	s_add_u32 s36, s36, 0x100
	s_addc_u32 s38, s38, 0
	s_cmp_gt_u32 s41, 13
	s_barrier
	s_cbranch_scc0 .LBB0_490
	s_branch .Lgemm_epi_b
	.p2align 6

; #define PG8_STAGE(bufoff, gbase, voff) do { _Pragma("unroll") for (int _i = 0; _i < 2; ++_i) \
;         __builtin_amdgcn_global_load_lds((const unsigned*)((const char*)(gbase) + (voff)[_i]), (LAS unsigned*)(lds + (bufoff) + ldsw + _i * 8192), 16, 0, 0); } while (0)
; #define PG8_LDA(dst, b, h) do { _Pragma("unroll") for (int m = 0; m < 4; ++m) _Pragma("unroll") for (int k = 0; k < 2; ++k) dst[m][k] = *(const LAS bf16x8*)(lds + PG8_SA(b, h) + aoff + m * 2048 + k * 1024); } while (0)
; #define PG8_LDB(dst, b, h) do { _Pragma("unroll") for (int n = 0; n < 2; ++n) _Pragma("unroll") for (int k = 0; k < 2; ++k) dst[n][k] = *(const LAS bf16x8*)(lds + PG8_SB(b, h) + boff + n * 2048 + k * 1024); } while (0)
; #define PG8_MMA(ai, bj, At, Bt) do { __builtin_amdgcn_s_setprio(1); _Pragma("unroll") for (int m = 0; m < 4; ++m) _Pragma("unroll") for (int n = 0; n < 2; ++n) _Pragma("unroll") for (int k = 0; k < 2; ++k) \
;         acc[ai][bj][m][n] = __builtin_amdgcn_mfma_f32_16x16x32_bf16(Bt[n][k], At[m][k], acc[ai][bj][m][n], 0, 0, 0); __builtin_amdgcn_s_setprio(0); } while (0)
; #define PG8_WAIT_L(n) asm volatile("s_waitcnt lgkmcnt(" #n ")" ::: "memory")
; template <class Epi>
; DI void gemm_phase(int wv, LAS unsigned char* lds, const GemmD g, const Epi& E) {
;     ...
;         const bool has_next = S.next(ui + 1, nxt);
;         const char* nA = has_next ? (const char*)g.A + (size_t)nxt.pm * 256 * g.lda * 2 : cA; const char* nB = has_next ? (const char*)g.Bt + PG8_BROW(nxt.pn) * (size_t)g.ldb * 2 : cB;
;         for (int t = 0; t < nt; t += 2) {
;             const bool last = (t == nt - 2);
;             const char* a1 = cA + (size_t)(t + 1) * kstep;
;             const char* a2 = last ? nA : cA + (size_t)(t + 2) * kstep; const char* b2 = last ? nB : cB + (size_t)(t + 2) * kstep;
;             const char* a3 = a2 + kstep; const char* b3 = b2 + kstep;
;             PG8_LDB(B0, 0, 0); PG8_SCHED; PG8_LDA(At, 0, 0); PG8_STAGE(PG8_SA(1, 1), a1 + hstepA, voffA);
;             PG8_WAIT_L(8); PG8_BAR; PG8_WAIT_L(0); PG8_MMA(0, 0, At, B0); PG8_BAR; PG8_SCHED;
;             PG8_LDB(B1, 0, 1); PG8_STAGE(PG8_SB(0, 0), b2, voffB);
;             PG8_BAR; PG8_WAIT_L(0); PG8_MMA(0, 1, At, B1); PG8_BAR;
;             PG8_LDA(At, 0, 1); PG8_STAGE(PG8_SA(0, 0), a2, voffA);
;             PG8_BAR; PG8_WAIT_L(0); PG8_MMA(1, 0, At, B0); PG8_BAR; PG8_SCHED;
.LBB0_543:
	s_ashr_i32 s23, s22, 31
	s_lshl_b64 s[18:19], s[22:23], s85
	v_cmp_lt_i64_e32 vcc, s[24:25], v[174:175]
	s_add_u32 s24, s81, s18
	s_addc_u32 s25, s80, s19
	s_and_b64 s[18:19], vcc, exec
	s_cselect_b32 s23, s25, s29
	s_cselect_b32 s68, s24, s28
	s_lshl_b32 s18, s55, 8
	s_ashr_i32 s19, s18, 31
	s_lshl_b64 s[18:19], s[18:19], s9
	s_add_u32 s26, s82, s18
	s_addc_u32 s27, s83, s19
	s_and_b64 s[18:19], vcc, exec
	s_cselect_b32 vcc_lo, s27, s31
	s_cselect_b32 vcc_hi, s26, s30
	s_add_u32 s28, s28, 0x80
	s_addc_u32 s29, s29, 0
	s_add_u32 s37, s30, 0x100
	s_addc_u32 s18, s31, 0
	s_mov_b32 s19, 0
	s_add_i32 s95, s19, 2
	s_add_u32 s2, s28, 0x80
	s_addc_u32 s3, s29, 0
	s_add_i32 s94, 0, 0x10000
	v_add_u32_e32 v145, s94, v141
	ds_read_b128 v[146:149], v145
	ds_read_b128 v[150:153], v145 offset:1024
	ds_read_b128 v[154:157], v145 offset:2048
	ds_read_b128 v[158:161], v145 offset:3072
	s_cmp_eq_u32 s17, s19
	s_cselect_b32 s31, s23, s3
	s_cselect_b32 s30, s68, s2
	s_cselect_b32 s35, vcc_lo, s18
	s_cselect_b32 s34, vcc_hi, s37
	v_lshl_add_u64 v[200:201], s[28:29], 0, v[136:137]
	s_add_i32 m0, s86, 0xc000
	ds_read_b128 v[162:165], v144
	ds_read_b128 v[168:171], v144 offset:1024
	ds_read_b128 v[176:179], v144 offset:2048
	ds_read_b128 v[180:183], v144 offset:3072
	ds_read_b128 v[184:187], v144 offset:4096
	ds_read_b128 v[188:191], v144 offset:5120
	ds_read_b128 v[192:195], v144 offset:6144
	ds_read_b128 v[196:199], v144 offset:7168
	global_load_lds_dwordx4 v[200:201], off
	v_lshl_add_u64 v[200:201], s[28:29], 0, v[138:139]
	s_add_i32 m0, s86, 0xe000
	s_nop 0
	global_load_lds_dwordx4 v[200:201], off
	s_waitcnt lgkmcnt(8)
	s_barrier
	s_waitcnt lgkmcnt(0)
	s_waitcnt lgkmcnt(0)
	v_mfma_f32_16x16x32_bf16 v[126:129], v[146:149], v[162:165], 0
	v_mfma_f32_16x16x32_bf16 v[122:125], v[154:157], v[162:165], 0
	v_mfma_f32_16x16x32_bf16 v[118:121], v[146:149], v[176:179], 0
	v_mfma_f32_16x16x32_bf16 v[114:117], v[154:157], v[176:179], 0
	v_mfma_f32_16x16x32_bf16 v[102:105], v[146:149], v[184:187], 0
	v_mfma_f32_16x16x32_bf16 v[98:101], v[154:157], v[184:187], 0
	v_mfma_f32_16x16x32_bf16 v[86:89], v[146:149], v[192:195], 0
	v_mfma_f32_16x16x32_bf16 v[82:85], v[154:157], v[192:195], 0
	v_mfma_f32_16x16x32_bf16 v[126:129], v[150:153], v[168:171], v[126:129]
	v_mfma_f32_16x16x32_bf16 v[122:125], v[158:161], v[168:171], v[122:125]
	v_mfma_f32_16x16x32_bf16 v[118:121], v[150:153], v[180:183], v[118:121]
	v_mfma_f32_16x16x32_bf16 v[114:117], v[158:161], v[180:183], v[114:117]
	v_mfma_f32_16x16x32_bf16 v[102:105], v[150:153], v[188:191], v[102:105]
	v_mfma_f32_16x16x32_bf16 v[98:101], v[158:161], v[188:191], v[98:101]
	v_mfma_f32_16x16x32_bf16 v[86:89], v[150:153], v[196:199], v[86:89]
	v_mfma_f32_16x16x32_bf16 v[82:85], v[158:161], v[196:199], v[82:85]
	s_barrier
	s_add_i32 s2, 0, 0x14000
	s_add_i32 s3, s94, s84
	v_add_u32_e32 v145, s2, v141
	v_lshl_add_u64 v[216:217], s[34:35], 0, v[0:1]
	s_mov_b32 m0, s3
	ds_read_b128 v[200:203], v145
	ds_read_b128 v[204:207], v145 offset:1024
	ds_read_b128 v[208:211], v145 offset:2048
	ds_read_b128 v[212:215], v145 offset:3072
	global_load_lds_dwordx4 v[216:217], off
	v_lshl_add_u64 v[218:219], s[34:35], 0, v[134:135]
	s_add_i32 m0, s3, 0x2000
	s_nop 0
	global_load_lds_dwordx4 v[218:219], off
	s_barrier
	s_waitcnt lgkmcnt(0)
	s_waitcnt lgkmcnt(0)
	v_mfma_f32_16x16x32_bf16 v[110:113], v[200:203], v[162:165], 0
	v_mfma_f32_16x16x32_bf16 v[106:109], v[208:211], v[162:165], 0
	v_mfma_f32_16x16x32_bf16 v[94:97], v[200:203], v[176:179], 0
	v_mfma_f32_16x16x32_bf16 v[90:93], v[208:211], v[176:179], 0
	v_mfma_f32_16x16x32_bf16 v[78:81], v[200:203], v[184:187], 0
	v_mfma_f32_16x16x32_bf16 v[74:77], v[208:211], v[184:187], 0
	v_mfma_f32_16x16x32_bf16 v[70:73], v[200:203], v[192:195], 0
	v_mfma_f32_16x16x32_bf16 v[66:69], v[208:211], v[192:195], 0
	v_mfma_f32_16x16x32_bf16 v[110:113], v[204:207], v[168:171], v[110:113]
	v_mfma_f32_16x16x32_bf16 v[106:109], v[212:215], v[168:171], v[106:109]
	v_mfma_f32_16x16x32_bf16 v[94:97], v[204:207], v[180:183], v[94:97]
	v_mfma_f32_16x16x32_bf16 v[90:93], v[212:215], v[180:183], v[90:93]
	v_mfma_f32_16x16x32_bf16 v[78:81], v[204:207], v[188:191], v[78:81]
	v_mfma_f32_16x16x32_bf16 v[74:77], v[212:215], v[188:191], v[74:77]
	v_mfma_f32_16x16x32_bf16 v[70:73], v[204:207], v[196:199], v[70:73]
	v_mfma_f32_16x16x32_bf16 v[66:69], v[212:215], v[196:199], v[66:69]
	s_mov_b32 m0, s86
	v_lshl_add_u64 v[220:221], s[30:31], 0, v[130:131]
	s_barrier
	ds_read_b128 v[162:165], v144 offset:16384
	ds_read_b128 v[168:171], v144 offset:17408
	ds_read_b128 v[176:179], v144 offset:18432
	ds_read_b128 v[180:183], v144 offset:19456
	ds_read_b128 v[184:187], v144 offset:20480
	ds_read_b128 v[188:191], v144 offset:21504
	ds_read_b128 v[192:195], v144 offset:22528
	ds_read_b128 v[196:199], v144 offset:23552
	global_load_lds_dwordx4 v[220:221], off
	v_lshl_add_u64 v[222:223], s[30:31], 0, v[132:133]
	s_mov_b32 m0, s87
	s_nop 0
	global_load_lds_dwordx4 v[222:223], off
	s_barrier
	s_waitcnt lgkmcnt(0)
	s_waitcnt lgkmcnt(0)
	v_mfma_f32_16x16x32_bf16 v[62:65], v[146:149], v[162:165], 0
	v_mfma_f32_16x16x32_bf16 v[58:61], v[154:157], v[162:165], 0
	v_mfma_f32_16x16x32_bf16 v[54:57], v[146:149], v[176:179], 0
	v_mfma_f32_16x16x32_bf16 v[50:53], v[154:157], v[176:179], 0
	v_mfma_f32_16x16x32_bf16 v[38:41], v[146:149], v[184:187], 0
	v_mfma_f32_16x16x32_bf16 v[34:37], v[154:157], v[184:187], 0
	v_mfma_f32_16x16x32_bf16 v[22:25], v[146:149], v[192:195], 0
	v_mfma_f32_16x16x32_bf16 v[18:21], v[154:157], v[192:195], 0
	v_mfma_f32_16x16x32_bf16 v[62:65], v[150:153], v[168:171], v[62:65]
	v_mfma_f32_16x16x32_bf16 v[58:61], v[158:161], v[168:171], v[58:61]
	v_mfma_f32_16x16x32_bf16 v[54:57], v[150:153], v[180:183], v[54:57]
	v_mfma_f32_16x16x32_bf16 v[50:53], v[158:161], v[180:183], v[50:53]
	v_mfma_f32_16x16x32_bf16 v[38:41], v[150:153], v[188:191], v[38:41]
	v_mfma_f32_16x16x32_bf16 v[34:37], v[158:161], v[188:191], v[34:37]
	v_mfma_f32_16x16x32_bf16 v[22:25], v[150:153], v[196:199], v[22:25]
	v_mfma_f32_16x16x32_bf16 v[18:21], v[158:161], v[196:199], v[18:21]
	s_barrier
; #define PG8_STAGE(bufoff, gbase, voff) do { _Pragma("unroll") for (int _i = 0; _i < 2; ++_i) \
;         __builtin_amdgcn_global_load_lds((const unsigned*)((const char*)(gbase) + (voff)[_i]), (LAS unsigned*)(lds + (bufoff) + ldsw + _i * 8192), 16, 0, 0); } while (0)
; #define PG8_LDA(dst, b, h) do { _Pragma("unroll") for (int m = 0; m < 4; ++m) _Pragma("unroll") for (int k = 0; k < 2; ++k) dst[m][k] = *(const LAS bf16x8*)(lds + PG8_SA(b, h) + aoff + m * 2048 + k * 1024); } while (0)
; #define PG8_LDB(dst, b, h) do { _Pragma("unroll") for (int n = 0; n < 2; ++n) _Pragma("unroll") for (int k = 0; k < 2; ++k) dst[n][k] = *(const LAS bf16x8*)(lds + PG8_SB(b, h) + boff + n * 2048 + k * 1024); } while (0)
; #define PG8_MMA(ai, bj, At, Bt) do { __builtin_amdgcn_s_setprio(1); _Pragma("unroll") for (int m = 0; m < 4; ++m) _Pragma("unroll") for (int n = 0; n < 2; ++n) _Pragma("unroll") for (int k = 0; k < 2; ++k) \
;         acc[ai][bj][m][n] = __builtin_amdgcn_mfma_f32_16x16x32_bf16(Bt[n][k], At[m][k], acc[ai][bj][m][n], 0, 0, 0); __builtin_amdgcn_s_setprio(0); } while (0)
; #define PG8_WAIT_V(n) asm volatile("s_waitcnt vmcnt(" #n ")" ::: "memory")
; #define PG8_WAIT_L(n) asm volatile("s_waitcnt lgkmcnt(" #n ")" ::: "memory")
; #define PG8_BAR __builtin_amdgcn_s_barrier()
; #define PG8_SCHED __builtin_amdgcn_sched_barrier(0)
; template <class Epi>
; DI void gemm_phase(int wv, LAS unsigned char* lds, const GemmD g, const Epi& E) {
;     ...
;             PG8_STAGE(PG8_SB(0, 1), b2 + hstepB, voffB);
;             PG8_WAIT_V(6); PG8_BAR; PG8_MMA(1, 1, At, B1); PG8_BAR;
;             PG8_LDB(B0, 1, 0); PG8_SCHED; PG8_LDA(At, 1, 0); PG8_STAGE(PG8_SA(0, 1), a2 + hstepA, voffA);
;             PG8_WAIT_L(8); PG8_BAR; PG8_WAIT_L(0); PG8_MMA(0, 0, At, B0); PG8_BAR; PG8_SCHED;
;             PG8_LDB(B1, 1, 1); PG8_STAGE(PG8_SB(1, 0), b3, voffB);
	s_add_u32 s34, s34, s56
	s_addc_u32 s35, s35, 0
	s_add_i32 s2, s2, s84
	v_lshl_add_u64 v[224:225], s[34:35], 0, v[0:1]
	s_mov_b32 m0, s2
	v_lshl_add_u64 v[226:227], s[34:35], 0, v[134:135]
	global_load_lds_dwordx4 v[224:225], off
	s_add_i32 m0, s2, 0x2000
	s_nop 0
	global_load_lds_dwordx4 v[226:227], off
	s_waitcnt vmcnt(6)
	s_barrier
	v_mfma_f32_16x16x32_bf16 v[46:49], v[200:203], v[162:165], 0
	v_mfma_f32_16x16x32_bf16 v[42:45], v[208:211], v[162:165], 0
	v_mfma_f32_16x16x32_bf16 v[30:33], v[200:203], v[176:179], 0
	v_mfma_f32_16x16x32_bf16 v[26:29], v[208:211], v[176:179], 0
	v_mfma_f32_16x16x32_bf16 v[14:17], v[200:203], v[184:187], 0
	v_mfma_f32_16x16x32_bf16 v[10:13], v[208:211], v[184:187], 0
	v_mfma_f32_16x16x32_bf16 v[6:9], v[200:203], v[192:195], 0
	v_mfma_f32_16x16x32_bf16 v[2:5], v[208:211], v[192:195], 0
	v_mfma_f32_16x16x32_bf16 v[46:49], v[204:207], v[168:171], v[46:49]
	v_mfma_f32_16x16x32_bf16 v[42:45], v[212:215], v[168:171], v[42:45]
	v_mfma_f32_16x16x32_bf16 v[30:33], v[204:207], v[180:183], v[30:33]
	v_mfma_f32_16x16x32_bf16 v[26:29], v[212:215], v[180:183], v[26:29]
	v_mfma_f32_16x16x32_bf16 v[14:17], v[204:207], v[188:191], v[14:17]
	v_mfma_f32_16x16x32_bf16 v[10:13], v[212:215], v[188:191], v[10:13]
	v_mfma_f32_16x16x32_bf16 v[6:9], v[204:207], v[196:199], v[6:9]
	v_mfma_f32_16x16x32_bf16 v[2:5], v[212:215], v[196:199], v[2:5]
	s_add_i32 s2, 0, 0x18000
	v_add_u32_e32 v145, s2, v141
	s_barrier
	ds_read_b128 v[146:149], v145
	ds_read_b128 v[150:153], v145 offset:1024
	ds_read_b128 v[154:157], v145 offset:2048
	ds_read_b128 v[158:161], v145 offset:3072
	s_add_u32 s30, s30, s56
	s_addc_u32 s31, s31, 0
	s_mov_b32 m0, s74
	v_lshl_add_u64 v[200:201], s[30:31], 0, v[130:131]
	ds_read_b128 v[162:165], v144 offset:32768
	ds_read_b128 v[168:171], v144 offset:33792
	ds_read_b128 v[176:179], v144 offset:34816
	ds_read_b128 v[180:183], v144 offset:35840
	ds_read_b128 v[184:187], v144 offset:36864
	ds_read_b128 v[188:191], v144 offset:37888
	ds_read_b128 v[192:195], v144 offset:38912
	ds_read_b128 v[196:199], v144 offset:39936
	global_load_lds_dwordx4 v[200:201], off
	v_lshl_add_u64 v[200:201], s[30:31], 0, v[132:133]
	s_mov_b32 m0, s41
	s_nop 0
	global_load_lds_dwordx4 v[200:201], off
	s_waitcnt lgkmcnt(8)
	s_barrier
	s_waitcnt lgkmcnt(0)
	s_waitcnt lgkmcnt(0)
	v_mfma_f32_16x16x32_bf16 v[126:129], v[146:149], v[162:165], v[126:129]
	v_mfma_f32_16x16x32_bf16 v[122:125], v[154:157], v[162:165], v[122:125]
	v_mfma_f32_16x16x32_bf16 v[118:121], v[146:149], v[176:179], v[118:121]
	v_mfma_f32_16x16x32_bf16 v[114:117], v[154:157], v[176:179], v[114:117]
	v_mfma_f32_16x16x32_bf16 v[102:105], v[146:149], v[184:187], v[102:105]
	v_mfma_f32_16x16x32_bf16 v[98:101], v[154:157], v[184:187], v[98:101]
	v_mfma_f32_16x16x32_bf16 v[86:89], v[146:149], v[192:195], v[86:89]
	v_mfma_f32_16x16x32_bf16 v[82:85], v[154:157], v[192:195], v[82:85]
	v_mfma_f32_16x16x32_bf16 v[126:129], v[150:153], v[168:171], v[126:129]
	v_mfma_f32_16x16x32_bf16 v[122:125], v[158:161], v[168:171], v[122:125]
	v_mfma_f32_16x16x32_bf16 v[118:121], v[150:153], v[180:183], v[118:121]
	v_mfma_f32_16x16x32_bf16 v[114:117], v[158:161], v[180:183], v[114:117]
	v_mfma_f32_16x16x32_bf16 v[102:105], v[150:153], v[188:191], v[102:105]
	v_mfma_f32_16x16x32_bf16 v[98:101], v[158:161], v[188:191], v[98:101]
	v_mfma_f32_16x16x32_bf16 v[86:89], v[150:153], v[196:199], v[86:89]
	v_mfma_f32_16x16x32_bf16 v[82:85], v[158:161], v[196:199], v[82:85]
	s_barrier
	s_add_i32 s3, 0, 0x1c000
	s_add_i32 s2, s2, s84
	v_add_u32_e32 v145, s3, v141
	v_lshl_add_u64 v[216:217], v[216:217], 0, s[58:59]
	s_mov_b32 m0, s2
	ds_read_b128 v[200:203], v145
	ds_read_b128 v[204:207], v145 offset:1024
	ds_read_b128 v[208:211], v145 offset:2048
	ds_read_b128 v[212:215], v145 offset:3072
	global_load_lds_dwordx4 v[216:217], off
	v_lshl_add_u64 v[216:217], v[218:219], 0, s[58:59]
	s_add_i32 m0, s2, 0x2000
	s_nop 0
	global_load_lds_dwordx4 v[216:217], off
	s_barrier
; #define PG8_STAGE(bufoff, gbase, voff) do { _Pragma("unroll") for (int _i = 0; _i < 2; ++_i) \
;         __builtin_amdgcn_global_load_lds((const unsigned*)((const char*)(gbase) + (voff)[_i]), (LAS unsigned*)(lds + (bufoff) + ldsw + _i * 8192), 16, 0, 0); } while (0)
; #define PG8_LDA(dst, b, h) do { _Pragma("unroll") for (int m = 0; m < 4; ++m) _Pragma("unroll") for (int k = 0; k < 2; ++k) dst[m][k] = *(const LAS bf16x8*)(lds + PG8_SA(b, h) + aoff + m * 2048 + k * 1024); } while (0)
; #define PG8_MMA(ai, bj, At, Bt) do { __builtin_amdgcn_s_setprio(1); _Pragma("unroll") for (int m = 0; m < 4; ++m) _Pragma("unroll") for (int n = 0; n < 2; ++n) _Pragma("unroll") for (int k = 0; k < 2; ++k) \
;         acc[ai][bj][m][n] = __builtin_amdgcn_mfma_f32_16x16x32_bf16(Bt[n][k], At[m][k], acc[ai][bj][m][n], 0, 0, 0); __builtin_amdgcn_s_setprio(0); } while (0)
; #define PG8_WAIT_V(n) asm volatile("s_waitcnt vmcnt(" #n ")" ::: "memory")
; #define PG8_WAIT_L(n) asm volatile("s_waitcnt lgkmcnt(" #n ")" ::: "memory")
; #define PG8_BAR __builtin_amdgcn_s_barrier()
; #define PG8_SCHED __builtin_amdgcn_sched_barrier(0)
; template <class Epi>
; DI void gemm_phase(int wv, LAS unsigned char* lds, const GemmD g, const Epi& E) {
;     ...
;             PG8_BAR; PG8_WAIT_L(0); PG8_MMA(0, 1, At, B1); PG8_BAR;
;             PG8_LDA(At, 1, 1); PG8_STAGE(PG8_SA(1, 0), a3, voffA);
;             PG8_BAR; PG8_WAIT_L(0); PG8_MMA(1, 0, At, B0); PG8_BAR; PG8_SCHED;
;             PG8_STAGE(PG8_SB(1, 1), b3 + hstepB, voffB);
;             PG8_WAIT_V(6); PG8_BAR; PG8_MMA(1, 1, At, B1); PG8_BAR;
;         }
	s_waitcnt lgkmcnt(0)
	s_waitcnt lgkmcnt(0)
	v_mfma_f32_16x16x32_bf16 v[110:113], v[200:203], v[162:165], v[110:113]
	v_mfma_f32_16x16x32_bf16 v[106:109], v[208:211], v[162:165], v[106:109]
	v_mfma_f32_16x16x32_bf16 v[94:97], v[200:203], v[176:179], v[94:97]
	v_mfma_f32_16x16x32_bf16 v[90:93], v[208:211], v[176:179], v[90:93]
	v_mfma_f32_16x16x32_bf16 v[78:81], v[200:203], v[184:187], v[78:81]
	v_mfma_f32_16x16x32_bf16 v[74:77], v[208:211], v[184:187], v[74:77]
	v_mfma_f32_16x16x32_bf16 v[70:73], v[200:203], v[192:195], v[70:73]
	v_mfma_f32_16x16x32_bf16 v[66:69], v[208:211], v[192:195], v[66:69]
	v_mfma_f32_16x16x32_bf16 v[110:113], v[204:207], v[168:171], v[110:113]
	v_mfma_f32_16x16x32_bf16 v[106:109], v[212:215], v[168:171], v[106:109]
	v_mfma_f32_16x16x32_bf16 v[94:97], v[204:207], v[180:183], v[94:97]
	v_mfma_f32_16x16x32_bf16 v[90:93], v[212:215], v[180:183], v[90:93]
	v_mfma_f32_16x16x32_bf16 v[78:81], v[204:207], v[188:191], v[78:81]
	v_mfma_f32_16x16x32_bf16 v[74:77], v[212:215], v[188:191], v[74:77]
	v_mfma_f32_16x16x32_bf16 v[70:73], v[204:207], v[196:199], v[70:73]
	v_mfma_f32_16x16x32_bf16 v[66:69], v[212:215], v[196:199], v[66:69]
	s_mov_b32 m0, s13
	v_lshl_add_u64 v[216:217], v[220:221], 0, s[58:59]
	s_barrier
	ds_read_b128 v[162:165], v144 offset:49152
	ds_read_b128 v[168:171], v144 offset:50176
	ds_read_b128 v[176:179], v144 offset:51200
	ds_read_b128 v[180:183], v144 offset:52224
	ds_read_b128 v[184:187], v144 offset:53248
	ds_read_b128 v[188:191], v144 offset:54272
	ds_read_b128 v[192:195], v144 offset:55296
	ds_read_b128 v[196:199], v144 offset:56320
	global_load_lds_dwordx4 v[216:217], off
	v_lshl_add_u64 v[216:217], v[222:223], 0, s[58:59]
	s_mov_b32 m0, s16
	s_nop 0
	global_load_lds_dwordx4 v[216:217], off
	s_barrier
	s_waitcnt lgkmcnt(0)
	s_waitcnt lgkmcnt(0)
	v_mfma_f32_16x16x32_bf16 v[62:65], v[146:149], v[162:165], v[62:65]
	v_mfma_f32_16x16x32_bf16 v[58:61], v[154:157], v[162:165], v[58:61]
	v_mfma_f32_16x16x32_bf16 v[54:57], v[146:149], v[176:179], v[54:57]
	v_mfma_f32_16x16x32_bf16 v[50:53], v[154:157], v[176:179], v[50:53]
	v_mfma_f32_16x16x32_bf16 v[38:41], v[146:149], v[184:187], v[38:41]
	v_mfma_f32_16x16x32_bf16 v[34:37], v[154:157], v[184:187], v[34:37]
	v_mfma_f32_16x16x32_bf16 v[22:25], v[146:149], v[192:195], v[22:25]
	v_mfma_f32_16x16x32_bf16 v[18:21], v[154:157], v[192:195], v[18:21]
	v_mfma_f32_16x16x32_bf16 v[62:65], v[150:153], v[168:171], v[62:65]
	v_mfma_f32_16x16x32_bf16 v[58:61], v[158:161], v[168:171], v[58:61]
	v_mfma_f32_16x16x32_bf16 v[54:57], v[150:153], v[180:183], v[54:57]
	v_mfma_f32_16x16x32_bf16 v[50:53], v[158:161], v[180:183], v[50:53]
	v_mfma_f32_16x16x32_bf16 v[38:41], v[150:153], v[188:191], v[38:41]
	v_mfma_f32_16x16x32_bf16 v[34:37], v[158:161], v[188:191], v[34:37]
	v_mfma_f32_16x16x32_bf16 v[22:25], v[150:153], v[196:199], v[22:25]
	v_mfma_f32_16x16x32_bf16 v[18:21], v[158:161], v[196:199], v[18:21]
	s_barrier
	s_add_i32 s2, s3, s84
	v_lshl_add_u64 v[146:147], v[224:225], 0, s[58:59]
	s_mov_b32 m0, s2
	s_nop 0
	global_load_lds_dwordx4 v[146:147], off
	v_lshl_add_u64 v[146:147], v[226:227], 0, s[58:59]
	s_add_i32 m0, s2, 0x2000
	s_nop 0
	global_load_lds_dwordx4 v[146:147], off
	s_waitcnt vmcnt(6)
	s_barrier
	v_mfma_f32_16x16x32_bf16 v[46:49], v[200:203], v[162:165], v[46:49]
	v_mfma_f32_16x16x32_bf16 v[42:45], v[208:211], v[162:165], v[42:45]
	v_mfma_f32_16x16x32_bf16 v[30:33], v[200:203], v[176:179], v[30:33]
	v_mfma_f32_16x16x32_bf16 v[26:29], v[208:211], v[176:179], v[26:29]
	v_mfma_f32_16x16x32_bf16 v[14:17], v[200:203], v[184:187], v[14:17]
	v_mfma_f32_16x16x32_bf16 v[10:13], v[208:211], v[184:187], v[10:13]
	v_mfma_f32_16x16x32_bf16 v[6:9], v[200:203], v[192:195], v[6:9]
	v_mfma_f32_16x16x32_bf16 v[2:5], v[208:211], v[192:195], v[2:5]
	v_mfma_f32_16x16x32_bf16 v[46:49], v[204:207], v[168:171], v[46:49]
	v_mfma_f32_16x16x32_bf16 v[42:45], v[212:215], v[168:171], v[42:45]
	v_mfma_f32_16x16x32_bf16 v[30:33], v[204:207], v[180:183], v[30:33]
	v_mfma_f32_16x16x32_bf16 v[26:29], v[212:215], v[180:183], v[26:29]
	v_mfma_f32_16x16x32_bf16 v[14:17], v[204:207], v[188:191], v[14:17]
	v_mfma_f32_16x16x32_bf16 v[10:13], v[212:215], v[188:191], v[10:13]
	v_mfma_f32_16x16x32_bf16 v[6:9], v[204:207], v[196:199], v[6:9]
	v_mfma_f32_16x16x32_bf16 v[2:5], v[212:215], v[196:199], v[2:5]
	s_add_u32 s28, s28, 0x100
	s_addc_u32 s29, s29, 0
	s_add_u32 s37, s37, 0x100
	s_addc_u32 s18, s18, 0
	s_cmp_ge_u32 s95, s38
	s_mov_b32 s19, s95
	s_barrier
	s_cbranch_scc0 .LBB0_544
	s_branch .Lgemm_epi_c
	.p2align 6
